# v85 + nt on the write-once f32 WU stores of s5_wu_phase (phase 3), leaving the memory-side cache to the scan operand tiles the GDN warmers fetch next
# speedup vs baseline: 1.0209x; 1.0131x over previous
; __device__ __forceinline__ f32x4 mfma16(bf16x8 a, bf16x8 b, f32x4 c) { return __builtin_amdgcn_mfma_f32_16x16x32_bf16(a, b, c, 0, 0, 0); }
; __device__ __forceinline__ void s5_wu_phase(const Ctx& F) {
;     ...
;     for (int task = gw; task < 64 * 64; task += NGW) {
;         const int g = task >> 6, c0 = (task & 63) * 16;
;         bf16x8 a[8];
; #pragma unroll
;         for (int ks = 0; ks < 8; ++ks) a[ks] = *(const bf16x8*)(UG + ((size_t)g * SEQ + (size_t)(c0 + fr) * 16) * 16 + ks * 32 + fq * 8);
;         const bf16_t* WT = WTb + (size_t)g * 128 * 256;
; #pragma unroll 2
;         for (int nt = 0; nt < 8; ++nt) {
;             f32x4 acc = (f32x4){0.f, 0.f, 0.f, 0.f};
; #pragma unroll
;             for (int ks = 0; ks < 8; ++ks) { const bf16x8 b = *(const bf16x8*)(WT + (size_t)(nt * 16 + fr) * 256 + ks * 32 + fq * 8); acc = mfma16(b, a[ks], acc); }
;             *(f32x4*)(WU + ((size_t)g * 1024 + c0 + fr) * 128 + nt * 16 + fq * 4) = acc;
;         }
;     }
.LBB0_820:
	v_lshl_add_u64 v[58:59], v[42:43], 0, v[36:37]
	s_nop 4
	v_lshl_add_u64 v[46:47], v[44:45], 0, v[36:37]
	v_add_co_u32_e32 v60, vcc, 0x1ec00000, v58
	v_add_co_u32_e64 v62, s[0:1], s13, v46
	s_nop 0
	v_addc_co_u32_e32 v61, vcc, 0, v59, vcc
	v_addc_co_u32_e64 v63, s[0:1], 0, v47, s[0:1]
	global_load_dwordx4 v[46:49], v[60:61], off
	global_load_dwordx4 v[50:53], v[60:61], off offset:64
	global_load_dwordx4 v[54:57], v[60:61], off offset:128
	v_add_co_u32_e32 v58, vcc, s14, v58
	s_add_i32 s15, s15, -2
	s_nop 0
	v_addc_co_u32_e32 v59, vcc, 0, v59, vcc
	v_lshl_add_u64 v[42:43], v[42:43], 0, s[4:5]
	v_lshl_add_u64 v[44:45], v[44:45], 0, s[6:7]
	s_cmp_lg_u32 s15, 0
	s_waitcnt vmcnt(0)
	v_mfma_f32_16x16x32_bf16 v[46:49], v[46:49], v[0:3], 0
	v_mfma_f32_16x16x32_bf16 v[46:49], v[50:53], v[4:7], v[46:49]
	global_load_dwordx4 v[50:53], v[60:61], off offset:192
	v_mfma_f32_16x16x32_bf16 v[46:49], v[54:57], v[8:11], v[46:49]
	global_load_dwordx4 v[54:57], v[60:61], off offset:256
	s_waitcnt vmcnt(1)
	v_mfma_f32_16x16x32_bf16 v[46:49], v[50:53], v[12:15], v[46:49]
	global_load_dwordx4 v[50:53], v[60:61], off offset:320
	s_waitcnt vmcnt(1)
	v_mfma_f32_16x16x32_bf16 v[46:49], v[54:57], v[16:19], v[46:49]
	global_load_dwordx4 v[54:57], v[60:61], off offset:384
	s_waitcnt vmcnt(1)
	v_mfma_f32_16x16x32_bf16 v[46:49], v[50:53], v[20:23], v[46:49]
	global_load_dwordx4 v[50:53], v[60:61], off offset:448
	s_waitcnt vmcnt(1)
	v_mfma_f32_16x16x32_bf16 v[46:49], v[54:57], v[24:27], v[46:49]
	s_waitcnt vmcnt(0)
	v_mfma_f32_16x16x32_bf16 v[46:49], v[50:53], v[28:31], v[46:49]
	s_nop 7
	global_store_dwordx4 v[62:63], v[46:49], off nt
	global_load_dwordx4 v[46:49], v[58:59], off
	s_nop 0
	global_load_dwordx4 v[50:53], v[58:59], off offset:64
	global_load_dwordx4 v[54:57], v[58:59], off offset:128
	s_waitcnt vmcnt(2)
	v_mfma_f32_16x16x32_bf16 v[46:49], v[46:49], v[0:3], 0
	s_waitcnt vmcnt(1)
	v_mfma_f32_16x16x32_bf16 v[46:49], v[50:53], v[4:7], v[46:49]
	global_load_dwordx4 v[50:53], v[58:59], off offset:192
	s_waitcnt vmcnt(1)
	v_mfma_f32_16x16x32_bf16 v[46:49], v[54:57], v[8:11], v[46:49]
	global_load_dwordx4 v[54:57], v[58:59], off offset:256
	s_waitcnt vmcnt(1)
	v_mfma_f32_16x16x32_bf16 v[46:49], v[50:53], v[12:15], v[46:49]
	global_load_dwordx4 v[50:53], v[58:59], off offset:320
	s_waitcnt vmcnt(1)
	v_mfma_f32_16x16x32_bf16 v[46:49], v[54:57], v[16:19], v[46:49]
	global_load_dwordx4 v[54:57], v[58:59], off offset:384
	s_waitcnt vmcnt(1)
	v_mfma_f32_16x16x32_bf16 v[46:49], v[50:53], v[20:23], v[46:49]
	global_load_dwordx4 v[50:53], v[58:59], off offset:448
	s_waitcnt vmcnt(1)
	v_mfma_f32_16x16x32_bf16 v[46:49], v[54:57], v[24:27], v[46:49]
	s_waitcnt vmcnt(0)
	v_mfma_f32_16x16x32_bf16 v[46:49], v[50:53], v[28:31], v[46:49]
	s_nop 7
	global_store_dwordx4 v[62:63], v[46:49], off offset:64 nt
	s_cbranch_scc1 .LBB0_820
	s_add_i32 s3, s3, s10
	s_add_i32 s11, s11, s12
	s_cmpk_gt_i32 s3, 0xfff
	s_cbranch_scc0 .LBB0_819
